# hyena epilogue: the lane's 128 consecutive u values fetched as two batches of eight 16-byte chunks; iterations 1..15 unpack from registers (no per-iteration vmcnt wait behind the previous stores)
# baseline (speedup 1.0000x reference)
; __device__ __forceinline__ float bf2f(u16 h) { return __uint_as_float(((unsigned)h) << 16); }
; __device__ __forceinline__ void hyena_lat_job(const Params& p, char* smem, int l, int c) {
;     ...
;     const float scale = rsqrtf(((const float*)(ws + OFF_FSS))[((l * 2 + 0) * 2 + o) * 256 + c] + EPSF);
;     const float skip = p.hy_skip[(l * 2 + o) * 256 + c];
;     const int gc = o * 256 + c;
;     const float w0 = cw[gc], w1 = cw[768 + gc], w2 = cw[1536 + gc], bb = cb[gc];
;     const u16* u = UT + (size_t)gc * MTOT + b * 8192;
;     __syncthreads();
;     int tb = 128 * ib + 4 * h;
;     asm volatile("" : "+v"(tb));
; #pragma unroll
;     for (int mt = 0; mt < 4; ++mt)
; #pragma unroll
;       for (int g = 0; g < 4; ++g) {
;         int t0 = tb + 32 * mt + 8 * g;
;         float uu[6];
;         {
;           const uint2 mid = *(const uint2*)&u[t0];
;           uu[0] = t0 > 0 ? bf2f(u[t0 - 1]) : 0.f;
;           uu[1] = __uint_as_float(mid.x << 16); uu[2] = __uint_as_float(mid.x & 0xffff0000u);
;           uu[3] = __uint_as_float(mid.y << 16); uu[4] = __uint_as_float(mid.y & 0xffff0000u);
;           uu[5] = t0 + 4 < 8192 ? bf2f(u[t0 + 4]) : 0.f;
;         }
;         const int zi0 = b * 10240 + (t0 >> 5) * 40 + (t0 & 31);
;         const uint2 zo = *(const uint2*)&zs[zi0];
;         float zold4[4] = {__uint_as_float(zo.x << 16), __uint_as_float(zo.x & 0xffff0000u),
;                           __uint_as_float(zo.y << 16), __uint_as_float(zo.y & 0xffff0000u)};
.LBB0_1017:
	s_or_b32 s14, s2, s29
	s_ashr_i32 s15, s14, 31
	s_lshl_b64 s[14:15], s[14:15], 2
	v_readlane_b32 s60, v239, 39
	s_add_u32 s14, s27, s14
	v_readlane_b32 s62, v239, 41
	v_readlane_b32 s63, v239, 42
	v_readlane_b32 s70, v239, 49
	v_readlane_b32 s71, v239, 50
	s_addc_u32 s15, s28, s15
	s_lshl_b64 s[0:1], s[0:1], 2
	s_mov_b64 s[62:63], s[70:71]
	s_add_u32 s0, s62, s0
	v_mov_b64_e32 v[66:67], s[14:15]
	s_addc_u32 s1, s63, s1
	s_or_b32 s2, s2, s10
	global_load_dword v0, v[66:67], off
	v_mov_b32_e32 v78, v129
	global_load_dword v66, v1, s[0:1]
	s_lshl_b64 s[0:1], s[2:3], 2
	s_add_u32 s14, s20, s0
	s_addc_u32 s15, s21, s1
	s_add_u32 s0, s22, s0
	s_addc_u32 s1, s23, s1
	global_load_dword v70, v1, s[14:15]
	global_load_dword v68, v1, s[14:15] offset:3072
	global_load_dword v72, v200, s[14:15] offset:2048
	global_load_dword v74, v1, s[0:1]
	v_mad_u64_u32 v[80:81], s[0:1], s2, v207, v[108:109]
	s_waitcnt lgkmcnt(0)
	s_barrier
	v_mov_b32_e32 v85, 0
	v_ashrrev_i32_e32 v79, 31, v78
	v_lshl_add_u64 v[76:77], v[78:79], 1, v[80:81]
	global_load_dwordx4 v[100:103], v[76:77], off offset:0
	global_load_dwordx4 v[224:227], v[76:77], off offset:16
	global_load_dwordx4 v[228:231], v[76:77], off offset:32
	global_load_dwordx4 v[232:235], v[76:77], off offset:48
	global_load_dwordx4 v[240:243], v[76:77], off offset:64
	global_load_dwordx4 v[246:249], v[76:77], off offset:80
	global_load_dwordx4 v[250:253], v[76:77], off offset:96
	global_load_dwordx2 v[104:105], v[76:77], off offset:112
	global_load_dwordx2 v[254:255], v[76:77], off offset:120
	global_load_dwordx2 v[82:83], v[76:77], off
	v_cmp_lt_i32_e64 s[0:1], 0, v78
	v_mov_b32_e32 v86, 0
	v_readlane_b32 s61, v239, 40
	v_readlane_b32 s64, v239, 43
	v_readlane_b32 s65, v239, 44
	v_readlane_b32 s66, v239, 45
	v_readlane_b32 s67, v239, 46
	v_readlane_b32 s68, v239, 47
	v_readlane_b32 s69, v239, 48
	v_readlane_b32 s72, v239, 51
	v_readlane_b32 s73, v239, 52
	v_readlane_b32 s74, v239, 53
	v_readlane_b32 s75, v239, 54
	s_waitcnt vmcnt(0)
	v_add_f32_e32 v0, 0x358637bd, v0
	v_cmp_gt_f32_e32 vcc, s92, v0
	s_and_saveexec_b64 s[14:15], s[0:1]
	s_cbranch_execz .LBB0_1019
	v_mov_b32_e32 v79, v1
	v_lshl_add_u64 v[86:87], v[78:79], 1, v[80:81]
	v_add_co_u32_e64 v86, s[0:1], -2, v86
	s_nop 1
	v_addc_co_u32_e64 v87, s[0:1], -1, v87, s[0:1]
	global_load_ushort v67, v[86:87], off
	s_waitcnt vmcnt(0) lgkmcnt(0)
	v_lshlrev_b32_e32 v86, 16, v67

; __device__ __forceinline__ float bf2f(u16 h) { return __uint_as_float(((unsigned)h) << 16); }
; __device__ __forceinline__ unsigned pack2(float a, float b) { return (unsigned)f2bf(a) | ((unsigned)f2bf(b) << 16); }
; __device__ __forceinline__ void hyena_lat_job(const Params& p, char* smem, int l, int c) {
;     ...
;         int t0 = tb + 32 * mt + 8 * g;
;         float uu[6];
;         {
;           const uint2 mid = *(const uint2*)&u[t0];
;           uu[0] = t0 > 0 ? bf2f(u[t0 - 1]) : 0.f;
;           uu[1] = __uint_as_float(mid.x << 16); uu[2] = __uint_as_float(mid.x & 0xffff0000u);
;           uu[3] = __uint_as_float(mid.y << 16); uu[4] = __uint_as_float(mid.y & 0xffff0000u);
;           uu[5] = t0 + 4 < 8192 ? bf2f(u[t0 + 4]) : 0.f;
;         }
;         const int zi0 = b * 10240 + (t0 >> 5) * 40 + (t0 & 31);
;         const uint2 zo = *(const uint2*)&zs[zi0];
;         float zold4[4] = {__uint_as_float(zo.x << 16), __uint_as_float(zo.x & 0xffff0000u),
;                           __uint_as_float(zo.y << 16), __uint_as_float(zo.y & 0xffff0000u)};
;         float zn4[4];
; #pragma unroll
;         for (int q = 0; q < 4; ++q) {
;           float gate = bb + w0 * uu[q] + w1 * uu[q + 1] + w2 * uu[q + 2];
;           zn4[q] = gate * (scale * acc[mt][g * 4 + q] + zold4[q] * skip);
;         }
;         if (o == 0) {
;           uint2 zw; zw.x = pack2(zn4[0], zn4[1]); zw.y = pack2(zn4[2], zn4[3]);
;           *(uint2*)&zs[zi0] = zw;
;         } else {
; #pragma unroll
;           for (int q = 0; q < 4; ++q) MIX[(size_t)(b * 8192 + t0 + q) * 1024 + 512 + c] = f2bf(zn4[q]);
;         }
.LBB0_1025:
	v_mov_b32_e32 v52, v224
	v_mov_b32_e32 v53, v225
	v_add_u32_e32 v0, 8, v78
	v_lshrrev_b32_e32 v244, 16, v103
	s_movk_i32 s0, 0x1ff4
	v_cmp_gt_i32_e32 vcc, s0, v78
	v_and_b32_e32 v245, 0xffff, v226
	s_nop 0
	v_cndmask_b32_e32 v245, 0, v245, vcc
	s_waitcnt lgkmcnt(0)
	v_lshlrev_b32_e32 v84, 16, v244
	v_lshlrev_b32_e32 v51, 16, v245
	v_and_b32_e32 v50, 31, v0
	v_ashrrev_i32_e32 v85, 5, v0
	v_mul_lo_u32 v85, v85, s54
	v_lshlrev_b32_e32 v86, 1, v50
	v_add3_u32 v87, v130, v85, v86
	ds_read_b64 v[94:95], v87
	s_waitcnt lgkmcnt(0)
	v_and_b32_e32 v92, 0xffff0000, v52
	v_mov_b32_e32 v71, v70
	v_mov_b32_e32 v75, v74
	v_mov_b32_e32 v85, v92
	v_mov_b32_e32 v69, v68
	v_lshlrev_b32_e32 v90, 16, v52
	v_lshlrev_b32_e32 v91, 16, v53
	v_pk_fma_f32 v[84:85], v[70:71], v[84:85], v[74:75]
	v_mov_b32_e32 v67, v66
	v_and_b32_e32 v93, 0xffff0000, v53
	v_mov_b32_e32 v50, v91
	v_lshlrev_b32_e32 v53, 16, v95
	v_lshlrev_b32_e32 v52, 16, v94
	v_and_b32_e32 v95, 0xffff0000, v95
	v_and_b32_e32 v94, 0xffff0000, v94
	v_pk_fma_f32 v[84:85], v[68:69], v[90:91], v[84:85]
	v_pk_fma_f32 v[90:91], v[70:71], v[90:91], v[74:75]
	v_mov_b32_e32 v73, v72
	v_mov_b32_e32 v83, v82
	v_mov_b32_e32 v96, v54
	v_mov_b32_e32 v97, v56
	v_pk_mul_f32 v[52:53], v[66:67], v[52:53]
	v_pk_fma_f32 v[90:91], v[68:69], v[92:93], v[90:91]
	v_mov_b32_e32 v56, v55
	v_pk_mul_f32 v[54:55], v[66:67], v[94:95]
	v_pk_fma_f32 v[84:85], v[72:73], v[92:93], v[84:85]
	v_pk_fma_f32 v[52:53], v[96:97], v[82:83], v[52:53]
	v_pk_fma_f32 v[50:51], v[72:73], v[50:51], v[90:91]
	v_pk_fma_f32 v[54:55], v[56:57], v[82:83], v[54:55]
	v_pk_mul_f32 v[52:53], v[84:85], v[52:53]
	v_pk_mul_f32 v[50:51], v[50:51], v[54:55]
	s_and_b64 vcc, exec, s[50:51]
	s_mov_b64 s[0:1], -1
	s_cbranch_vccnz .LBB0_1031
	v_add_u32_e32 v54, v0, v128
	v_ashrrev_i32_e32 v55, 31, v54
	v_bfe_u32 v0, v52, 16, 1
	v_lshlrev_b64 v[54:55], 11, v[54:55]
	v_add3_u32 v0, v52, v0, s33
	v_lshl_add_u64 v[54:55], s[4:5], 0, v[54:55]
	global_store_short_d16_hi v[54:55], v0, off
	v_bfe_u32 v0, v50, 16, 1
	v_add3_u32 v0, v50, v0, s33
	global_store_short_d16_hi v[54:55], v0, off offset:2048
	v_bfe_u32 v0, v53, 16, 1
	v_add_co_u32_e32 v54, vcc, 0x1000, v54
	v_add3_u32 v0, v53, v0, s33
	s_nop 0
	v_addc_co_u32_e32 v55, vcc, 0, v55, vcc
	global_store_short_d16_hi v[54:55], v0, off
	v_bfe_u32 v0, v51, 16, 1
	v_add3_u32 v0, v51, v0, s33
	s_mov_b64 s[0:1], 0
	global_store_short_d16_hi v[54:55], v0, off offset:2048

; __device__ __forceinline__ float bf2f(u16 h) { return __uint_as_float(((unsigned)h) << 16); }
; __device__ __forceinline__ unsigned pack2(float a, float b) { return (unsigned)f2bf(a) | ((unsigned)f2bf(b) << 16); }
; __device__ __forceinline__ void hyena_lat_job(const Params& p, char* smem, int l, int c) {
;     ...
;         int t0 = tb + 32 * mt + 8 * g;
;         float uu[6];
;         {
;           const uint2 mid = *(const uint2*)&u[t0];
;           uu[0] = t0 > 0 ? bf2f(u[t0 - 1]) : 0.f;
;           uu[1] = __uint_as_float(mid.x << 16); uu[2] = __uint_as_float(mid.x & 0xffff0000u);
;           uu[3] = __uint_as_float(mid.y << 16); uu[4] = __uint_as_float(mid.y & 0xffff0000u);
;           uu[5] = t0 + 4 < 8192 ? bf2f(u[t0 + 4]) : 0.f;
;         }
;         const int zi0 = b * 10240 + (t0 >> 5) * 40 + (t0 & 31);
;         const uint2 zo = *(const uint2*)&zs[zi0];
;         float zold4[4] = {__uint_as_float(zo.x << 16), __uint_as_float(zo.x & 0xffff0000u),
;                           __uint_as_float(zo.y << 16), __uint_as_float(zo.y & 0xffff0000u)};
;         float zn4[4];
; #pragma unroll
;         for (int q = 0; q < 4; ++q) {
;           float gate = bb + w0 * uu[q] + w1 * uu[q + 1] + w2 * uu[q + 2];
;           zn4[q] = gate * (scale * acc[mt][g * 4 + q] + zold4[q] * skip);
;         }
;         if (o == 0) {
;           uint2 zw; zw.x = pack2(zn4[0], zn4[1]); zw.y = pack2(zn4[2], zn4[3]);
;           *(uint2*)&zs[zi0] = zw;
;         } else {
; #pragma unroll
;           for (int q = 0; q < 4; ++q) MIX[(size_t)(b * 8192 + t0 + q) * 1024 + 512 + c] = f2bf(zn4[q]);
;         }
.LBB0_1033:
	v_mov_b32_e32 v52, v228
	v_mov_b32_e32 v53, v229
	v_add_u32_e32 v0, 16, v78
	v_lshrrev_b32_e32 v244, 16, v227
	s_movk_i32 s0, 0x1fec
	v_cmp_gt_i32_e32 vcc, s0, v78
	v_and_b32_e32 v245, 0xffff, v230
	s_nop 0
	v_cndmask_b32_e32 v245, 0, v245, vcc
	s_waitcnt lgkmcnt(0)
	v_lshlrev_b32_e32 v54, 16, v244
	v_lshlrev_b32_e32 v51, 16, v245
	v_xor_b32_e32 v50, 16, v88
	v_ashrrev_i32_e32 v55, 5, v0
	v_mul_lo_u32 v55, v55, s54
	v_lshlrev_b32_e32 v56, 1, v50
	v_add3_u32 v57, v130, v55, v56
	ds_read_b64 v[90:91], v57
	s_waitcnt lgkmcnt(0)
	v_and_b32_e32 v88, 0xffff0000, v52
	v_mov_b32_e32 v55, v88
	v_lshlrev_b32_e32 v84, 16, v52
	v_lshlrev_b32_e32 v85, 16, v53
	v_pk_fma_f32 v[54:55], v[70:71], v[54:55], v[74:75]
	v_and_b32_e32 v89, 0xffff0000, v53
	v_mov_b32_e32 v50, v85
	v_lshlrev_b32_e32 v53, 16, v91
	v_lshlrev_b32_e32 v52, 16, v90
	v_and_b32_e32 v91, 0xffff0000, v91
	v_and_b32_e32 v90, 0xffff0000, v90
	v_pk_fma_f32 v[54:55], v[68:69], v[84:85], v[54:55]
	v_pk_fma_f32 v[84:85], v[70:71], v[84:85], v[74:75]
	v_mov_b32_e32 v92, v58
	v_mov_b32_e32 v93, v60
	v_pk_mul_f32 v[52:53], v[66:67], v[52:53]
	v_pk_fma_f32 v[84:85], v[68:69], v[88:89], v[84:85]
	v_mov_b32_e32 v60, v59
	v_pk_mul_f32 v[58:59], v[66:67], v[90:91]
	v_pk_fma_f32 v[54:55], v[72:73], v[88:89], v[54:55]
	v_pk_fma_f32 v[52:53], v[92:93], v[82:83], v[52:53]
	v_pk_fma_f32 v[50:51], v[72:73], v[50:51], v[84:85]
	v_pk_fma_f32 v[58:59], v[60:61], v[82:83], v[58:59]
	v_pk_mul_f32 v[52:53], v[54:55], v[52:53]
	v_pk_mul_f32 v[50:51], v[50:51], v[58:59]
	s_and_b64 vcc, exec, s[50:51]
	s_mov_b64 s[0:1], -1
	s_cbranch_vccnz .LBB0_1039
	v_add_u32_e32 v54, v0, v128
	v_ashrrev_i32_e32 v55, 31, v54
	v_bfe_u32 v0, v52, 16, 1
	v_lshlrev_b64 v[54:55], 11, v[54:55]
	v_add3_u32 v0, v52, v0, s33
	v_lshl_add_u64 v[54:55], s[4:5], 0, v[54:55]
	global_store_short_d16_hi v[54:55], v0, off
	v_bfe_u32 v0, v50, 16, 1
	v_add3_u32 v0, v50, v0, s33
	global_store_short_d16_hi v[54:55], v0, off offset:2048
	v_bfe_u32 v0, v53, 16, 1
	v_add_co_u32_e32 v54, vcc, 0x1000, v54
	v_add3_u32 v0, v53, v0, s33
	s_nop 0
	v_addc_co_u32_e32 v55, vcc, 0, v55, vcc
	global_store_short_d16_hi v[54:55], v0, off
	v_bfe_u32 v0, v51, 16, 1
	v_add3_u32 v0, v51, v0, s33
	s_mov_b64 s[0:1], 0
	global_store_short_d16_hi v[54:55], v0, off offset:2048

; __device__ __forceinline__ float bf2f(u16 h) { return __uint_as_float(((unsigned)h) << 16); }
; __device__ __forceinline__ unsigned pack2(float a, float b) { return (unsigned)f2bf(a) | ((unsigned)f2bf(b) << 16); }
; __device__ __forceinline__ void hyena_lat_job(const Params& p, char* smem, int l, int c) {
;     ...
;         int t0 = tb + 32 * mt + 8 * g;
;         float uu[6];
;         {
;           const uint2 mid = *(const uint2*)&u[t0];
;           uu[0] = t0 > 0 ? bf2f(u[t0 - 1]) : 0.f;
;           uu[1] = __uint_as_float(mid.x << 16); uu[2] = __uint_as_float(mid.x & 0xffff0000u);
;           uu[3] = __uint_as_float(mid.y << 16); uu[4] = __uint_as_float(mid.y & 0xffff0000u);
;           uu[5] = t0 + 4 < 8192 ? bf2f(u[t0 + 4]) : 0.f;
;         }
;         const int zi0 = b * 10240 + (t0 >> 5) * 40 + (t0 & 31);
;         const uint2 zo = *(const uint2*)&zs[zi0];
;         float zold4[4] = {__uint_as_float(zo.x << 16), __uint_as_float(zo.x & 0xffff0000u),
;                           __uint_as_float(zo.y << 16), __uint_as_float(zo.y & 0xffff0000u)};
;         float zn4[4];
; #pragma unroll
;         for (int q = 0; q < 4; ++q) {
;           float gate = bb + w0 * uu[q] + w1 * uu[q + 1] + w2 * uu[q + 2];
;           zn4[q] = gate * (scale * acc[mt][g * 4 + q] + zold4[q] * skip);
;         }
;         if (o == 0) {
;           uint2 zw; zw.x = pack2(zn4[0], zn4[1]); zw.y = pack2(zn4[2], zn4[3]);
;           *(uint2*)&zs[zi0] = zw;
;         } else {
; #pragma unroll
;           for (int q = 0; q < 4; ++q) MIX[(size_t)(b * 8192 + t0 + q) * 1024 + 512 + c] = f2bf(zn4[q]);
;         }
.LBB0_1041:
	v_mov_b32_e32 v52, v232
	v_mov_b32_e32 v53, v233
	v_add_u32_e32 v0, 24, v78
	v_lshrrev_b32_e32 v244, 16, v231
	s_movk_i32 s0, 0x1fe4
	v_cmp_gt_i32_e32 vcc, s0, v78
	v_and_b32_e32 v245, 0xffff, v234
	s_nop 0
	v_cndmask_b32_e32 v245, 0, v245, vcc
	s_waitcnt lgkmcnt(0)
	v_lshlrev_b32_e32 v54, 16, v244
	v_lshlrev_b32_e32 v51, 16, v245
	v_and_b32_e32 v50, 31, v0
	v_ashrrev_i32_e32 v55, 5, v0
	v_mul_lo_u32 v55, v55, s54
	v_lshlrev_b32_e32 v57, 1, v50
	v_add3_u32 v58, v130, v55, v57
	ds_read_b64 v[88:89], v58
	s_waitcnt lgkmcnt(0)
	v_and_b32_e32 v84, 0xffff0000, v52
	v_mov_b32_e32 v55, v84
	v_lshlrev_b32_e32 v60, 16, v52
	v_lshlrev_b32_e32 v61, 16, v53
	v_pk_fma_f32 v[54:55], v[70:71], v[54:55], v[74:75]
	v_and_b32_e32 v85, 0xffff0000, v53
	v_mov_b32_e32 v50, v61
	v_pk_fma_f32 v[54:55], v[68:69], v[60:61], v[54:55]
	v_pk_fma_f32 v[60:61], v[70:71], v[60:61], v[74:75]
	v_lshlrev_b32_e32 v53, 16, v89
	v_lshlrev_b32_e32 v52, 16, v88
	v_and_b32_e32 v89, 0xffff0000, v89
	v_and_b32_e32 v88, 0xffff0000, v88
	v_pk_fma_f32 v[60:61], v[68:69], v[84:85], v[60:61]
	v_mov_b32_e32 v90, v62
	v_mov_b32_e32 v91, v64
	v_pk_mul_f32 v[52:53], v[66:67], v[52:53]
	v_pk_fma_f32 v[50:51], v[72:73], v[50:51], v[60:61]
	v_mov_b32_e32 v64, v63
	v_pk_mul_f32 v[60:61], v[66:67], v[88:89]
	v_pk_fma_f32 v[54:55], v[72:73], v[84:85], v[54:55]
	v_pk_fma_f32 v[52:53], v[90:91], v[82:83], v[52:53]
	v_pk_fma_f32 v[60:61], v[64:65], v[82:83], v[60:61]
	v_pk_mul_f32 v[52:53], v[54:55], v[52:53]
	v_pk_mul_f32 v[50:51], v[50:51], v[60:61]
	s_and_b64 vcc, exec, s[50:51]
	s_mov_b64 s[0:1], -1
	s_cbranch_vccnz .LBB0_1047
	v_add_u32_e32 v54, v0, v128
	v_ashrrev_i32_e32 v55, 31, v54
	v_bfe_u32 v0, v52, 16, 1
	v_lshlrev_b64 v[54:55], 11, v[54:55]
	v_add3_u32 v0, v52, v0, s33
	v_lshl_add_u64 v[54:55], s[4:5], 0, v[54:55]
	global_store_short_d16_hi v[54:55], v0, off
	v_bfe_u32 v0, v50, 16, 1
	v_add3_u32 v0, v50, v0, s33
	global_store_short_d16_hi v[54:55], v0, off offset:2048
	v_bfe_u32 v0, v53, 16, 1
	v_add_co_u32_e32 v54, vcc, 0x1000, v54
	v_add3_u32 v0, v53, v0, s33
	s_nop 0
	v_addc_co_u32_e32 v55, vcc, 0, v55, vcc
	global_store_short_d16_hi v[54:55], v0, off
	v_bfe_u32 v0, v51, 16, 1
	v_add3_u32 v0, v51, v0, s33
	s_mov_b64 s[0:1], 0
	global_store_short_d16_hi v[54:55], v0, off offset:2048

; __device__ __forceinline__ float bf2f(u16 h) { return __uint_as_float(((unsigned)h) << 16); }
; __device__ __forceinline__ unsigned pack2(float a, float b) { return (unsigned)f2bf(a) | ((unsigned)f2bf(b) << 16); }
; __device__ __forceinline__ void hyena_lat_job(const Params& p, char* smem, int l, int c) {
;     ...
;         int t0 = tb + 32 * mt + 8 * g;
;         float uu[6];
;         {
;           const uint2 mid = *(const uint2*)&u[t0];
;           uu[0] = t0 > 0 ? bf2f(u[t0 - 1]) : 0.f;
;           uu[1] = __uint_as_float(mid.x << 16); uu[2] = __uint_as_float(mid.x & 0xffff0000u);
;           uu[3] = __uint_as_float(mid.y << 16); uu[4] = __uint_as_float(mid.y & 0xffff0000u);
;           uu[5] = t0 + 4 < 8192 ? bf2f(u[t0 + 4]) : 0.f;
;         }
;         const int zi0 = b * 10240 + (t0 >> 5) * 40 + (t0 & 31);
;         const uint2 zo = *(const uint2*)&zs[zi0];
;         float zold4[4] = {__uint_as_float(zo.x << 16), __uint_as_float(zo.x & 0xffff0000u),
;                           __uint_as_float(zo.y << 16), __uint_as_float(zo.y & 0xffff0000u)};
;         float zn4[4];
; #pragma unroll
;         for (int q = 0; q < 4; ++q) {
;           float gate = bb + w0 * uu[q] + w1 * uu[q + 1] + w2 * uu[q + 2];
;           zn4[q] = gate * (scale * acc[mt][g * 4 + q] + zold4[q] * skip);
;         }
;         if (o == 0) {
;           uint2 zw; zw.x = pack2(zn4[0], zn4[1]); zw.y = pack2(zn4[2], zn4[3]);
;           *(uint2*)&zs[zi0] = zw;
;         } else {
; #pragma unroll
;           for (int q = 0; q < 4; ++q) MIX[(size_t)(b * 8192 + t0 + q) * 1024 + 512 + c] = f2bf(zn4[q]);
;         }
.LBB0_1049:
	v_mov_b32_e32 v52, v240
	v_mov_b32_e32 v53, v241
	v_add_u32_e32 v0, 32, v78
	v_lshrrev_b32_e32 v244, 16, v235
	s_movk_i32 s0, 0x1fdc
	v_cmp_gt_i32_e32 vcc, s0, v78
	v_and_b32_e32 v245, 0xffff, v242
	s_nop 0
	v_cndmask_b32_e32 v245, 0, v245, vcc
	s_waitcnt lgkmcnt(0)
	v_lshlrev_b32_e32 v54, 16, v244
	v_lshlrev_b32_e32 v51, 16, v245
	v_ashrrev_i32_e32 v50, 5, v0
	v_mul_lo_u32 v50, v50, s54
	v_add3_u32 v58, v130, v50, v79
	ds_read_b64 v[64:65], v58
	s_waitcnt lgkmcnt(0)
	v_and_b32_e32 v62, 0xffff0000, v52
	v_mov_b32_e32 v55, v62
	v_lshlrev_b32_e32 v60, 16, v52
	v_lshlrev_b32_e32 v61, 16, v53
	v_pk_fma_f32 v[54:55], v[70:71], v[54:55], v[74:75]
	v_and_b32_e32 v63, 0xffff0000, v53
	v_mov_b32_e32 v50, v61
	v_lshlrev_b32_e32 v53, 16, v65
	v_lshlrev_b32_e32 v52, 16, v64
	v_and_b32_e32 v65, 0xffff0000, v65
	v_and_b32_e32 v64, 0xffff0000, v64
	v_pk_fma_f32 v[54:55], v[68:69], v[60:61], v[54:55]
	v_pk_fma_f32 v[60:61], v[70:71], v[60:61], v[74:75]
	v_mov_b32_e32 v84, v34
	v_mov_b32_e32 v85, v36
	v_pk_mul_f32 v[52:53], v[66:67], v[52:53]
	v_pk_fma_f32 v[60:61], v[68:69], v[62:63], v[60:61]
	v_mov_b32_e32 v36, v35
	v_pk_mul_f32 v[34:35], v[66:67], v[64:65]
	v_pk_fma_f32 v[54:55], v[72:73], v[62:63], v[54:55]
	v_pk_fma_f32 v[52:53], v[84:85], v[82:83], v[52:53]
	v_pk_fma_f32 v[50:51], v[72:73], v[50:51], v[60:61]
	v_pk_fma_f32 v[34:35], v[36:37], v[82:83], v[34:35]
	v_pk_mul_f32 v[36:37], v[54:55], v[52:53]
	v_pk_mul_f32 v[34:35], v[50:51], v[34:35]
	s_and_b64 vcc, exec, s[50:51]
	s_mov_b64 s[0:1], -1
	s_cbranch_vccnz .LBB0_1055
	v_add_u32_e32 v50, v0, v128
	v_ashrrev_i32_e32 v51, 31, v50
	v_bfe_u32 v0, v36, 16, 1
	v_lshlrev_b64 v[50:51], 11, v[50:51]
	v_add3_u32 v0, v36, v0, s33
	v_lshl_add_u64 v[50:51], s[4:5], 0, v[50:51]
	global_store_short_d16_hi v[50:51], v0, off
	v_bfe_u32 v0, v34, 16, 1
	v_add3_u32 v0, v34, v0, s33
	global_store_short_d16_hi v[50:51], v0, off offset:2048
	v_bfe_u32 v0, v37, 16, 1
	v_add_co_u32_e32 v50, vcc, 0x1000, v50
	v_add3_u32 v0, v37, v0, s33
	s_nop 0
	v_addc_co_u32_e32 v51, vcc, 0, v51, vcc
	global_store_short_d16_hi v[50:51], v0, off
	v_bfe_u32 v0, v35, 16, 1
	v_add3_u32 v0, v35, v0, s33
	s_mov_b64 s[0:1], 0
	global_store_short_d16_hi v[50:51], v0, off offset:2048

; __device__ __forceinline__ float bf2f(u16 h) { return __uint_as_float(((unsigned)h) << 16); }
; __device__ __forceinline__ unsigned pack2(float a, float b) { return (unsigned)f2bf(a) | ((unsigned)f2bf(b) << 16); }
; __device__ __forceinline__ void hyena_lat_job(const Params& p, char* smem, int l, int c) {
;     ...
;         int t0 = tb + 32 * mt + 8 * g;
;         float uu[6];
;         {
;           const uint2 mid = *(const uint2*)&u[t0];
;           uu[0] = t0 > 0 ? bf2f(u[t0 - 1]) : 0.f;
;           uu[1] = __uint_as_float(mid.x << 16); uu[2] = __uint_as_float(mid.x & 0xffff0000u);
;           uu[3] = __uint_as_float(mid.y << 16); uu[4] = __uint_as_float(mid.y & 0xffff0000u);
;           uu[5] = t0 + 4 < 8192 ? bf2f(u[t0 + 4]) : 0.f;
;         }
;         const int zi0 = b * 10240 + (t0 >> 5) * 40 + (t0 & 31);
;         const uint2 zo = *(const uint2*)&zs[zi0];
;         float zold4[4] = {__uint_as_float(zo.x << 16), __uint_as_float(zo.x & 0xffff0000u),
;                           __uint_as_float(zo.y << 16), __uint_as_float(zo.y & 0xffff0000u)};
;         float zn4[4];
; #pragma unroll
;         for (int q = 0; q < 4; ++q) {
;           float gate = bb + w0 * uu[q] + w1 * uu[q + 1] + w2 * uu[q + 2];
;           zn4[q] = gate * (scale * acc[mt][g * 4 + q] + zold4[q] * skip);
;         }
;         if (o == 0) {
;           uint2 zw; zw.x = pack2(zn4[0], zn4[1]); zw.y = pack2(zn4[2], zn4[3]);
;           *(uint2*)&zs[zi0] = zw;
;         } else {
; #pragma unroll
;           for (int q = 0; q < 4; ++q) MIX[(size_t)(b * 8192 + t0 + q) * 1024 + 512 + c] = f2bf(zn4[q]);
;         }
.LBB0_1057:
	v_mov_b32_e32 v36, v246
	v_mov_b32_e32 v37, v247
	v_add_u32_e32 v0, 40, v78
	v_lshrrev_b32_e32 v244, 16, v243
	s_movk_i32 s0, 0x1fd4
	v_cmp_gt_i32_e32 vcc, s0, v78
	v_and_b32_e32 v245, 0xffff, v248
	s_nop 0
	v_cndmask_b32_e32 v245, 0, v245, vcc
	s_waitcnt lgkmcnt(0)
	v_lshlrev_b32_e32 v50, 16, v244
	v_lshlrev_b32_e32 v35, 16, v245
	v_ashrrev_i32_e32 v34, 5, v0
	v_mul_lo_u32 v34, v34, s54
	v_add3_u32 v52, v130, v34, v86
	ds_read_b64 v[60:61], v52
	s_waitcnt lgkmcnt(0)
	v_and_b32_e32 v58, 0xffff0000, v36
	v_mov_b32_e32 v51, v58
	v_lshlrev_b32_e32 v54, 16, v36
	v_lshlrev_b32_e32 v55, 16, v37
	v_pk_fma_f32 v[50:51], v[70:71], v[50:51], v[74:75]
	v_and_b32_e32 v59, 0xffff0000, v37
	v_mov_b32_e32 v34, v55
	v_lshlrev_b32_e32 v37, 16, v61
	v_lshlrev_b32_e32 v36, 16, v60
	v_and_b32_e32 v61, 0xffff0000, v61
	v_and_b32_e32 v60, 0xffff0000, v60
	v_pk_fma_f32 v[50:51], v[68:69], v[54:55], v[50:51]
	v_pk_fma_f32 v[54:55], v[70:71], v[54:55], v[74:75]
	v_mov_b32_e32 v62, v38
	v_mov_b32_e32 v63, v40
	v_pk_mul_f32 v[36:37], v[66:67], v[36:37]
	v_pk_fma_f32 v[54:55], v[68:69], v[58:59], v[54:55]
	v_mov_b32_e32 v40, v39
	v_pk_mul_f32 v[38:39], v[66:67], v[60:61]
	v_pk_fma_f32 v[50:51], v[72:73], v[58:59], v[50:51]
	v_pk_fma_f32 v[36:37], v[62:63], v[82:83], v[36:37]
	v_pk_fma_f32 v[34:35], v[72:73], v[34:35], v[54:55]
	v_pk_fma_f32 v[38:39], v[40:41], v[82:83], v[38:39]
	v_pk_mul_f32 v[36:37], v[50:51], v[36:37]
	v_pk_mul_f32 v[34:35], v[34:35], v[38:39]
	s_and_b64 vcc, exec, s[50:51]
	s_mov_b64 s[0:1], -1
	s_cbranch_vccnz .LBB0_1063
	v_add_u32_e32 v38, v0, v128
	v_ashrrev_i32_e32 v39, 31, v38
	v_bfe_u32 v0, v36, 16, 1
	v_lshlrev_b64 v[38:39], 11, v[38:39]
	v_add3_u32 v0, v36, v0, s33
	v_lshl_add_u64 v[38:39], s[4:5], 0, v[38:39]
	global_store_short_d16_hi v[38:39], v0, off
	v_bfe_u32 v0, v34, 16, 1
	v_add3_u32 v0, v34, v0, s33
	global_store_short_d16_hi v[38:39], v0, off offset:2048
	v_bfe_u32 v0, v37, 16, 1
	v_add_co_u32_e32 v38, vcc, 0x1000, v38
	v_add3_u32 v0, v37, v0, s33
	s_nop 0
	v_addc_co_u32_e32 v39, vcc, 0, v39, vcc
	global_store_short_d16_hi v[38:39], v0, off
	v_bfe_u32 v0, v35, 16, 1
	v_add3_u32 v0, v35, v0, s33
	s_mov_b64 s[0:1], 0
	global_store_short_d16_hi v[38:39], v0, off offset:2048

; __device__ __forceinline__ float bf2f(u16 h) { return __uint_as_float(((unsigned)h) << 16); }
; __device__ __forceinline__ unsigned pack2(float a, float b) { return (unsigned)f2bf(a) | ((unsigned)f2bf(b) << 16); }
; __device__ __forceinline__ void hyena_lat_job(const Params& p, char* smem, int l, int c) {
;     ...
;         int t0 = tb + 32 * mt + 8 * g;
;         float uu[6];
;         {
;           const uint2 mid = *(const uint2*)&u[t0];
;           uu[0] = t0 > 0 ? bf2f(u[t0 - 1]) : 0.f;
;           uu[1] = __uint_as_float(mid.x << 16); uu[2] = __uint_as_float(mid.x & 0xffff0000u);
;           uu[3] = __uint_as_float(mid.y << 16); uu[4] = __uint_as_float(mid.y & 0xffff0000u);
;           uu[5] = t0 + 4 < 8192 ? bf2f(u[t0 + 4]) : 0.f;
;         }
;         const int zi0 = b * 10240 + (t0 >> 5) * 40 + (t0 & 31);
;         const uint2 zo = *(const uint2*)&zs[zi0];
;         float zold4[4] = {__uint_as_float(zo.x << 16), __uint_as_float(zo.x & 0xffff0000u),
;                           __uint_as_float(zo.y << 16), __uint_as_float(zo.y & 0xffff0000u)};
;         float zn4[4];
; #pragma unroll
;         for (int q = 0; q < 4; ++q) {
;           float gate = bb + w0 * uu[q] + w1 * uu[q + 1] + w2 * uu[q + 2];
;           zn4[q] = gate * (scale * acc[mt][g * 4 + q] + zold4[q] * skip);
;         }
;         if (o == 0) {
;           uint2 zw; zw.x = pack2(zn4[0], zn4[1]); zw.y = pack2(zn4[2], zn4[3]);
;           *(uint2*)&zs[zi0] = zw;
;         } else {
; #pragma unroll
;           for (int q = 0; q < 4; ++q) MIX[(size_t)(b * 8192 + t0 + q) * 1024 + 512 + c] = f2bf(zn4[q]);
;         }
.LBB0_1065:
	v_mov_b32_e32 v36, v250
	v_mov_b32_e32 v37, v251
	v_add_u32_e32 v0, 48, v78
	v_lshrrev_b32_e32 v244, 16, v249
	s_movk_i32 s0, 0x1fcc
	v_cmp_gt_i32_e32 vcc, s0, v78
	v_and_b32_e32 v245, 0xffff, v252
	s_nop 0
	v_cndmask_b32_e32 v245, 0, v245, vcc
	s_waitcnt lgkmcnt(0)
	v_lshlrev_b32_e32 v38, 16, v244
	v_lshlrev_b32_e32 v35, 16, v245
	v_ashrrev_i32_e32 v34, 5, v0
	v_mul_lo_u32 v34, v34, s54
	v_add3_u32 v40, v130, v34, v56
	ds_read_b64 v[54:55], v40
	s_waitcnt lgkmcnt(0)
	v_and_b32_e32 v52, 0xffff0000, v36
	v_mov_b32_e32 v39, v52
	v_lshlrev_b32_e32 v50, 16, v36
	v_lshlrev_b32_e32 v51, 16, v37
	v_pk_fma_f32 v[38:39], v[70:71], v[38:39], v[74:75]
	v_and_b32_e32 v53, 0xffff0000, v37
	v_mov_b32_e32 v34, v51
	v_lshlrev_b32_e32 v37, 16, v55
	v_lshlrev_b32_e32 v36, 16, v54
	v_and_b32_e32 v55, 0xffff0000, v55
	v_and_b32_e32 v54, 0xffff0000, v54
	v_pk_fma_f32 v[38:39], v[68:69], v[50:51], v[38:39]
	v_pk_fma_f32 v[50:51], v[70:71], v[50:51], v[74:75]
	v_mov_b32_e32 v58, v42
	v_mov_b32_e32 v59, v44
	v_pk_mul_f32 v[36:37], v[66:67], v[36:37]
	v_pk_fma_f32 v[50:51], v[68:69], v[52:53], v[50:51]
	v_mov_b32_e32 v44, v43
	v_pk_mul_f32 v[42:43], v[66:67], v[54:55]
	v_pk_fma_f32 v[38:39], v[72:73], v[52:53], v[38:39]
	v_pk_fma_f32 v[36:37], v[58:59], v[82:83], v[36:37]
	v_pk_fma_f32 v[34:35], v[72:73], v[34:35], v[50:51]
	v_pk_fma_f32 v[42:43], v[44:45], v[82:83], v[42:43]
	v_pk_mul_f32 v[36:37], v[38:39], v[36:37]
	v_pk_mul_f32 v[34:35], v[34:35], v[42:43]
	s_and_b64 vcc, exec, s[50:51]
	s_mov_b64 s[0:1], -1
	s_cbranch_vccnz .LBB0_1071
	v_add_u32_e32 v38, v0, v128
	v_ashrrev_i32_e32 v39, 31, v38
	v_bfe_u32 v0, v36, 16, 1
	v_lshlrev_b64 v[38:39], 11, v[38:39]
	v_add3_u32 v0, v36, v0, s33
	v_lshl_add_u64 v[38:39], s[4:5], 0, v[38:39]
	global_store_short_d16_hi v[38:39], v0, off
	v_bfe_u32 v0, v34, 16, 1
	v_add3_u32 v0, v34, v0, s33
	global_store_short_d16_hi v[38:39], v0, off offset:2048
	v_bfe_u32 v0, v37, 16, 1
	v_add_co_u32_e32 v38, vcc, 0x1000, v38
	v_add3_u32 v0, v37, v0, s33
	s_nop 0
	v_addc_co_u32_e32 v39, vcc, 0, v39, vcc
	global_store_short_d16_hi v[38:39], v0, off
	v_bfe_u32 v0, v35, 16, 1
	v_add3_u32 v0, v35, v0, s33
	s_mov_b64 s[0:1], 0
	global_store_short_d16_hi v[38:39], v0, off offset:2048

; __device__ __forceinline__ float bf2f(u16 h) { return __uint_as_float(((unsigned)h) << 16); }
; __device__ __forceinline__ unsigned pack2(float a, float b) { return (unsigned)f2bf(a) | ((unsigned)f2bf(b) << 16); }
; __device__ __forceinline__ void hyena_lat_job(const Params& p, char* smem, int l, int c) {
;     ...
;         int t0 = tb + 32 * mt + 8 * g;
;         float uu[6];
;         {
;           const uint2 mid = *(const uint2*)&u[t0];
;           uu[0] = t0 > 0 ? bf2f(u[t0 - 1]) : 0.f;
;           uu[1] = __uint_as_float(mid.x << 16); uu[2] = __uint_as_float(mid.x & 0xffff0000u);
;           uu[3] = __uint_as_float(mid.y << 16); uu[4] = __uint_as_float(mid.y & 0xffff0000u);
;           uu[5] = t0 + 4 < 8192 ? bf2f(u[t0 + 4]) : 0.f;
;         }
;         const int zi0 = b * 10240 + (t0 >> 5) * 40 + (t0 & 31);
;         const uint2 zo = *(const uint2*)&zs[zi0];
;         float zold4[4] = {__uint_as_float(zo.x << 16), __uint_as_float(zo.x & 0xffff0000u),
;                           __uint_as_float(zo.y << 16), __uint_as_float(zo.y & 0xffff0000u)};
;         float zn4[4];
; #pragma unroll
;         for (int q = 0; q < 4; ++q) {
;           float gate = bb + w0 * uu[q] + w1 * uu[q + 1] + w2 * uu[q + 2];
;           zn4[q] = gate * (scale * acc[mt][g * 4 + q] + zold4[q] * skip);
;         }
;         if (o == 0) {
;           uint2 zw; zw.x = pack2(zn4[0], zn4[1]); zw.y = pack2(zn4[2], zn4[3]);
;           *(uint2*)&zs[zi0] = zw;
;         } else {
; #pragma unroll
;           for (int q = 0; q < 4; ++q) MIX[(size_t)(b * 8192 + t0 + q) * 1024 + 512 + c] = f2bf(zn4[q]);
;         }
.LBB0_1073:
	v_mov_b32_e32 v36, v104
	v_mov_b32_e32 v37, v105
	v_add_u32_e32 v0, 56, v78
	v_lshrrev_b32_e32 v244, 16, v253
	s_movk_i32 s0, 0x1fc4
	v_cmp_gt_i32_e32 vcc, s0, v78
	v_and_b32_e32 v245, 0xffff, v254
	s_nop 0
	v_cndmask_b32_e32 v245, 0, v245, vcc
	s_waitcnt lgkmcnt(0)
	v_lshlrev_b32_e32 v38, 16, v244
	v_lshlrev_b32_e32 v35, 16, v245
	v_ashrrev_i32_e32 v34, 5, v0
	v_mul_lo_u32 v34, v34, s54
	v_add3_u32 v40, v130, v34, v57
	ds_read_b64 v[50:51], v40
	s_waitcnt lgkmcnt(0)
	v_and_b32_e32 v44, 0xffff0000, v36
	v_mov_b32_e32 v39, v44
	v_lshlrev_b32_e32 v42, 16, v36
	v_lshlrev_b32_e32 v43, 16, v37
	v_pk_fma_f32 v[38:39], v[70:71], v[38:39], v[74:75]
	v_and_b32_e32 v45, 0xffff0000, v37
	v_mov_b32_e32 v34, v43
	v_pk_fma_f32 v[38:39], v[68:69], v[42:43], v[38:39]
	v_pk_fma_f32 v[42:43], v[70:71], v[42:43], v[74:75]
	v_lshlrev_b32_e32 v37, 16, v51
	v_lshlrev_b32_e32 v36, 16, v50
	v_and_b32_e32 v51, 0xffff0000, v51
	v_and_b32_e32 v50, 0xffff0000, v50
	v_pk_fma_f32 v[42:43], v[68:69], v[44:45], v[42:43]
	v_mov_b32_e32 v52, v46
	v_mov_b32_e32 v53, v48
	v_pk_mul_f32 v[36:37], v[66:67], v[36:37]
	v_pk_fma_f32 v[34:35], v[72:73], v[34:35], v[42:43]
	v_mov_b32_e32 v48, v47
	v_pk_mul_f32 v[42:43], v[66:67], v[50:51]
	v_pk_fma_f32 v[38:39], v[72:73], v[44:45], v[38:39]
	v_pk_fma_f32 v[36:37], v[52:53], v[82:83], v[36:37]
	v_pk_fma_f32 v[42:43], v[48:49], v[82:83], v[42:43]
	v_pk_mul_f32 v[36:37], v[38:39], v[36:37]
	v_pk_mul_f32 v[34:35], v[34:35], v[42:43]
	s_and_b64 vcc, exec, s[50:51]
	s_mov_b64 s[0:1], -1
	s_cbranch_vccnz .LBB0_1079
	v_add_u32_e32 v38, v0, v128
	v_ashrrev_i32_e32 v39, 31, v38
	v_bfe_u32 v0, v36, 16, 1
	v_lshlrev_b64 v[38:39], 11, v[38:39]
	v_add3_u32 v0, v36, v0, s33
	v_lshl_add_u64 v[38:39], s[4:5], 0, v[38:39]
	global_store_short_d16_hi v[38:39], v0, off
	v_bfe_u32 v0, v34, 16, 1
	v_add3_u32 v0, v34, v0, s33
	global_store_short_d16_hi v[38:39], v0, off offset:2048
	v_bfe_u32 v0, v37, 16, 1
	v_add_co_u32_e32 v38, vcc, 0x1000, v38
	v_add3_u32 v0, v37, v0, s33
	s_nop 0
	v_addc_co_u32_e32 v39, vcc, 0, v39, vcc
	global_store_short_d16_hi v[38:39], v0, off
	v_bfe_u32 v0, v35, 16, 1
	v_add3_u32 v0, v35, v0, s33
	s_mov_b64 s[0:1], 0
	global_store_short_d16_hi v[38:39], v0, off offset:2048

; __device__ __forceinline__ float bf2f(u16 h) { return __uint_as_float(((unsigned)h) << 16); }
; __device__ __forceinline__ unsigned pack2(float a, float b) { return (unsigned)f2bf(a) | ((unsigned)f2bf(b) << 16); }
; __device__ __forceinline__ void hyena_lat_job(const Params& p, char* smem, int l, int c) {
;     ...
;         int t0 = tb + 32 * mt + 8 * g;
;         float uu[6];
;         {
;           const uint2 mid = *(const uint2*)&u[t0];
;           uu[0] = t0 > 0 ? bf2f(u[t0 - 1]) : 0.f;
;           uu[1] = __uint_as_float(mid.x << 16); uu[2] = __uint_as_float(mid.x & 0xffff0000u);
;           uu[3] = __uint_as_float(mid.y << 16); uu[4] = __uint_as_float(mid.y & 0xffff0000u);
;           uu[5] = t0 + 4 < 8192 ? bf2f(u[t0 + 4]) : 0.f;
;         }
;         const int zi0 = b * 10240 + (t0 >> 5) * 40 + (t0 & 31);
;         const uint2 zo = *(const uint2*)&zs[zi0];
;         float zold4[4] = {__uint_as_float(zo.x << 16), __uint_as_float(zo.x & 0xffff0000u),
;                           __uint_as_float(zo.y << 16), __uint_as_float(zo.y & 0xffff0000u)};
;         float zn4[4];
; #pragma unroll
;         for (int q = 0; q < 4; ++q) {
;           float gate = bb + w0 * uu[q] + w1 * uu[q + 1] + w2 * uu[q + 2];
;           zn4[q] = gate * (scale * acc[mt][g * 4 + q] + zold4[q] * skip);
;         }
;         if (o == 0) {
;           uint2 zw; zw.x = pack2(zn4[0], zn4[1]); zw.y = pack2(zn4[2], zn4[3]);
;           *(uint2*)&zs[zi0] = zw;
;         } else {
; #pragma unroll
;           for (int q = 0; q < 4; ++q) MIX[(size_t)(b * 8192 + t0 + q) * 1024 + 512 + c] = f2bf(zn4[q]);
;         }
.LBB0_1081:
	v_and_b32_e32 v38, 0xffff0000, v255
	global_load_dwordx4 v[100:103], v[76:77], off offset:128
	global_load_dwordx4 v[224:227], v[76:77], off offset:144
	global_load_dwordx4 v[228:231], v[76:77], off offset:160
	global_load_dwordx4 v[232:235], v[76:77], off offset:176
	global_load_dwordx4 v[240:243], v[76:77], off offset:192
	global_load_dwordx4 v[246:249], v[76:77], off offset:208
	global_load_dwordx4 v[250:253], v[76:77], off offset:224
	global_load_dwordx2 v[104:105], v[76:77], off offset:240
	global_load_dwordx2 v[254:255], v[76:77], off offset:248
	s_waitcnt vmcnt(0)
	v_mov_b32_e32 v36, v100
	v_mov_b32_e32 v37, v101
	v_add_u32_e32 v0, 64, v78
	s_movk_i32 s0, 0x1fbc
	v_cmp_gt_i32_e32 vcc, s0, v78
	v_lshlrev_b32_e32 v35, 16, v102
	s_nop 0
	v_cndmask_b32_e32 v35, 0, v35, vcc
	v_ashrrev_i32_e32 v34, 5, v0
	v_mul_lo_u32 v34, v34, s54
	v_add3_u32 v40, v130, v34, v79
	ds_read_b64 v[46:47], v40
	s_waitcnt lgkmcnt(0)
	v_and_b32_e32 v44, 0xffff0000, v36
	v_mov_b32_e32 v39, v44
	v_lshlrev_b32_e32 v42, 16, v36
	v_lshlrev_b32_e32 v43, 16, v37
	v_pk_fma_f32 v[38:39], v[70:71], v[38:39], v[74:75]
	v_and_b32_e32 v45, 0xffff0000, v37
	v_mov_b32_e32 v34, v43
	v_lshlrev_b32_e32 v37, 16, v47
	v_lshlrev_b32_e32 v36, 16, v46
	v_and_b32_e32 v47, 0xffff0000, v47
	v_and_b32_e32 v46, 0xffff0000, v46
	v_pk_fma_f32 v[38:39], v[68:69], v[42:43], v[38:39]
	v_pk_fma_f32 v[42:43], v[70:71], v[42:43], v[74:75]
	v_mov_b32_e32 v48, v18
	v_mov_b32_e32 v49, v20
	v_pk_mul_f32 v[36:37], v[66:67], v[36:37]
	v_pk_fma_f32 v[42:43], v[68:69], v[44:45], v[42:43]
	v_mov_b32_e32 v20, v19
	v_pk_mul_f32 v[18:19], v[66:67], v[46:47]
	v_pk_fma_f32 v[38:39], v[72:73], v[44:45], v[38:39]
	v_pk_fma_f32 v[36:37], v[48:49], v[82:83], v[36:37]
	v_pk_fma_f32 v[34:35], v[72:73], v[34:35], v[42:43]
	v_pk_fma_f32 v[18:19], v[20:21], v[82:83], v[18:19]
	v_pk_mul_f32 v[20:21], v[38:39], v[36:37]
	v_pk_mul_f32 v[18:19], v[34:35], v[18:19]
	s_and_b64 vcc, exec, s[50:51]
	s_mov_b64 s[0:1], -1
	s_cbranch_vccnz .LBB0_1087
	v_add_u32_e32 v34, v0, v128
	v_ashrrev_i32_e32 v35, 31, v34
	v_bfe_u32 v0, v20, 16, 1
	v_lshlrev_b64 v[34:35], 11, v[34:35]
	v_add3_u32 v0, v20, v0, s33
	v_lshl_add_u64 v[34:35], s[4:5], 0, v[34:35]
	global_store_short_d16_hi v[34:35], v0, off
	v_bfe_u32 v0, v18, 16, 1
	v_add3_u32 v0, v18, v0, s33
	global_store_short_d16_hi v[34:35], v0, off offset:2048
	v_bfe_u32 v0, v21, 16, 1
	v_add_co_u32_e32 v34, vcc, 0x1000, v34
	v_add3_u32 v0, v21, v0, s33
	s_nop 0
	v_addc_co_u32_e32 v35, vcc, 0, v35, vcc
	global_store_short_d16_hi v[34:35], v0, off
	v_bfe_u32 v0, v19, 16, 1
	v_add3_u32 v0, v19, v0, s33
	s_mov_b64 s[0:1], 0
	global_store_short_d16_hi v[34:35], v0, off offset:2048

; __device__ __forceinline__ float bf2f(u16 h) { return __uint_as_float(((unsigned)h) << 16); }
; __device__ __forceinline__ unsigned pack2(float a, float b) { return (unsigned)f2bf(a) | ((unsigned)f2bf(b) << 16); }
; __device__ __forceinline__ void hyena_lat_job(const Params& p, char* smem, int l, int c) {
;     ...
;         int t0 = tb + 32 * mt + 8 * g;
;         float uu[6];
;         {
;           const uint2 mid = *(const uint2*)&u[t0];
;           uu[0] = t0 > 0 ? bf2f(u[t0 - 1]) : 0.f;
;           uu[1] = __uint_as_float(mid.x << 16); uu[2] = __uint_as_float(mid.x & 0xffff0000u);
;           uu[3] = __uint_as_float(mid.y << 16); uu[4] = __uint_as_float(mid.y & 0xffff0000u);
;           uu[5] = t0 + 4 < 8192 ? bf2f(u[t0 + 4]) : 0.f;
;         }
;         const int zi0 = b * 10240 + (t0 >> 5) * 40 + (t0 & 31);
;         const uint2 zo = *(const uint2*)&zs[zi0];
;         float zold4[4] = {__uint_as_float(zo.x << 16), __uint_as_float(zo.x & 0xffff0000u),
;                           __uint_as_float(zo.y << 16), __uint_as_float(zo.y & 0xffff0000u)};
;         float zn4[4];
; #pragma unroll
;         for (int q = 0; q < 4; ++q) {
;           float gate = bb + w0 * uu[q] + w1 * uu[q + 1] + w2 * uu[q + 2];
;           zn4[q] = gate * (scale * acc[mt][g * 4 + q] + zold4[q] * skip);
;         }
;         if (o == 0) {
;           uint2 zw; zw.x = pack2(zn4[0], zn4[1]); zw.y = pack2(zn4[2], zn4[3]);
;           *(uint2*)&zs[zi0] = zw;
;         } else {
; #pragma unroll
;           for (int q = 0; q < 4; ++q) MIX[(size_t)(b * 8192 + t0 + q) * 1024 + 512 + c] = f2bf(zn4[q]);
;         }
.LBB0_1089:
	v_mov_b32_e32 v20, v224
	v_mov_b32_e32 v21, v225
	v_add_u32_e32 v0, 72, v78
	v_lshrrev_b32_e32 v244, 16, v103
	s_movk_i32 s0, 0x1fb4
	v_cmp_gt_i32_e32 vcc, s0, v78
	v_and_b32_e32 v245, 0xffff, v226
	s_nop 0
	v_cndmask_b32_e32 v245, 0, v245, vcc
	s_waitcnt lgkmcnt(0)
	v_lshlrev_b32_e32 v34, 16, v244
	v_lshlrev_b32_e32 v19, 16, v245
	v_ashrrev_i32_e32 v18, 5, v0
	v_mul_lo_u32 v18, v18, s54
	v_add3_u32 v36, v130, v18, v86
	ds_read_b64 v[42:43], v36
	s_waitcnt lgkmcnt(0)
	v_and_b32_e32 v40, 0xffff0000, v20
	v_mov_b32_e32 v35, v40
	v_lshlrev_b32_e32 v38, 16, v20
	v_lshlrev_b32_e32 v39, 16, v21
	v_pk_fma_f32 v[34:35], v[70:71], v[34:35], v[74:75]
	v_and_b32_e32 v41, 0xffff0000, v21
	v_mov_b32_e32 v18, v39
	v_lshlrev_b32_e32 v21, 16, v43
	v_lshlrev_b32_e32 v20, 16, v42
	v_and_b32_e32 v43, 0xffff0000, v43
	v_and_b32_e32 v42, 0xffff0000, v42
	v_pk_fma_f32 v[34:35], v[68:69], v[38:39], v[34:35]
	v_pk_fma_f32 v[38:39], v[70:71], v[38:39], v[74:75]
	v_mov_b32_e32 v44, v22
	v_mov_b32_e32 v45, v24
	v_pk_mul_f32 v[20:21], v[66:67], v[20:21]
	v_pk_fma_f32 v[38:39], v[68:69], v[40:41], v[38:39]
	v_mov_b32_e32 v24, v23
	v_pk_mul_f32 v[22:23], v[66:67], v[42:43]
	v_pk_fma_f32 v[34:35], v[72:73], v[40:41], v[34:35]
	v_pk_fma_f32 v[20:21], v[44:45], v[82:83], v[20:21]
	v_pk_fma_f32 v[18:19], v[72:73], v[18:19], v[38:39]
	v_pk_fma_f32 v[22:23], v[24:25], v[82:83], v[22:23]
	v_pk_mul_f32 v[20:21], v[34:35], v[20:21]
	v_pk_mul_f32 v[18:19], v[18:19], v[22:23]
	s_and_b64 vcc, exec, s[50:51]
	s_mov_b64 s[0:1], -1
	s_cbranch_vccnz .LBB0_1095
	v_add_u32_e32 v22, v0, v128
	v_ashrrev_i32_e32 v23, 31, v22
	v_bfe_u32 v0, v20, 16, 1
	v_lshlrev_b64 v[22:23], 11, v[22:23]
	v_add3_u32 v0, v20, v0, s33
	v_lshl_add_u64 v[22:23], s[4:5], 0, v[22:23]
	global_store_short_d16_hi v[22:23], v0, off
	v_bfe_u32 v0, v18, 16, 1
	v_add3_u32 v0, v18, v0, s33
	global_store_short_d16_hi v[22:23], v0, off offset:2048
	v_bfe_u32 v0, v21, 16, 1
	v_add_co_u32_e32 v22, vcc, 0x1000, v22
	v_add3_u32 v0, v21, v0, s33
	s_nop 0
	v_addc_co_u32_e32 v23, vcc, 0, v23, vcc
	global_store_short_d16_hi v[22:23], v0, off
	v_bfe_u32 v0, v19, 16, 1
	v_add3_u32 v0, v19, v0, s33
	s_mov_b64 s[0:1], 0
	global_store_short_d16_hi v[22:23], v0, off offset:2048

; __device__ __forceinline__ float bf2f(u16 h) { return __uint_as_float(((unsigned)h) << 16); }
; __device__ __forceinline__ unsigned pack2(float a, float b) { return (unsigned)f2bf(a) | ((unsigned)f2bf(b) << 16); }
; __device__ __forceinline__ void hyena_lat_job(const Params& p, char* smem, int l, int c) {
;     ...
;         int t0 = tb + 32 * mt + 8 * g;
;         float uu[6];
;         {
;           const uint2 mid = *(const uint2*)&u[t0];
;           uu[0] = t0 > 0 ? bf2f(u[t0 - 1]) : 0.f;
;           uu[1] = __uint_as_float(mid.x << 16); uu[2] = __uint_as_float(mid.x & 0xffff0000u);
;           uu[3] = __uint_as_float(mid.y << 16); uu[4] = __uint_as_float(mid.y & 0xffff0000u);
;           uu[5] = t0 + 4 < 8192 ? bf2f(u[t0 + 4]) : 0.f;
;         }
;         const int zi0 = b * 10240 + (t0 >> 5) * 40 + (t0 & 31);
;         const uint2 zo = *(const uint2*)&zs[zi0];
;         float zold4[4] = {__uint_as_float(zo.x << 16), __uint_as_float(zo.x & 0xffff0000u),
;                           __uint_as_float(zo.y << 16), __uint_as_float(zo.y & 0xffff0000u)};
;         float zn4[4];
; #pragma unroll
;         for (int q = 0; q < 4; ++q) {
;           float gate = bb + w0 * uu[q] + w1 * uu[q + 1] + w2 * uu[q + 2];
;           zn4[q] = gate * (scale * acc[mt][g * 4 + q] + zold4[q] * skip);
;         }
;         if (o == 0) {
;           uint2 zw; zw.x = pack2(zn4[0], zn4[1]); zw.y = pack2(zn4[2], zn4[3]);
;           *(uint2*)&zs[zi0] = zw;
;         } else {
; #pragma unroll
;           for (int q = 0; q < 4; ++q) MIX[(size_t)(b * 8192 + t0 + q) * 1024 + 512 + c] = f2bf(zn4[q]);
;         }
.LBB0_1097:
	v_mov_b32_e32 v20, v228
	v_mov_b32_e32 v21, v229
	v_add_u32_e32 v0, 80, v78
	v_lshrrev_b32_e32 v244, 16, v227
	s_movk_i32 s0, 0x1fac
	v_cmp_gt_i32_e32 vcc, s0, v78
	v_and_b32_e32 v245, 0xffff, v230
	s_nop 0
	v_cndmask_b32_e32 v245, 0, v245, vcc
	s_waitcnt lgkmcnt(0)
	v_lshlrev_b32_e32 v22, 16, v244
	v_lshlrev_b32_e32 v19, 16, v245
	v_ashrrev_i32_e32 v18, 5, v0
	v_mul_lo_u32 v18, v18, s54
	v_add3_u32 v24, v130, v18, v56
	ds_read_b64 v[38:39], v24
	s_waitcnt lgkmcnt(0)
	v_and_b32_e32 v36, 0xffff0000, v20
	v_mov_b32_e32 v23, v36
	v_lshlrev_b32_e32 v34, 16, v20
	v_lshlrev_b32_e32 v35, 16, v21
	v_pk_fma_f32 v[22:23], v[70:71], v[22:23], v[74:75]
	v_and_b32_e32 v37, 0xffff0000, v21
	v_mov_b32_e32 v18, v35
	v_lshlrev_b32_e32 v21, 16, v39
	v_lshlrev_b32_e32 v20, 16, v38
	v_and_b32_e32 v39, 0xffff0000, v39
	v_and_b32_e32 v38, 0xffff0000, v38
	v_pk_fma_f32 v[22:23], v[68:69], v[34:35], v[22:23]
	v_pk_fma_f32 v[34:35], v[70:71], v[34:35], v[74:75]
	v_mov_b32_e32 v40, v26
	v_mov_b32_e32 v41, v28
	v_pk_mul_f32 v[20:21], v[66:67], v[20:21]
	v_pk_fma_f32 v[34:35], v[68:69], v[36:37], v[34:35]
	v_mov_b32_e32 v28, v27
	v_pk_mul_f32 v[26:27], v[66:67], v[38:39]
	v_pk_fma_f32 v[22:23], v[72:73], v[36:37], v[22:23]
	v_pk_fma_f32 v[20:21], v[40:41], v[82:83], v[20:21]
	v_pk_fma_f32 v[18:19], v[72:73], v[18:19], v[34:35]
	v_pk_fma_f32 v[26:27], v[28:29], v[82:83], v[26:27]
	v_pk_mul_f32 v[20:21], v[22:23], v[20:21]
	v_pk_mul_f32 v[18:19], v[18:19], v[26:27]
	s_and_b64 vcc, exec, s[50:51]
	s_mov_b64 s[0:1], -1
	s_cbranch_vccnz .LBB0_1103
	v_add_u32_e32 v22, v0, v128
	v_ashrrev_i32_e32 v23, 31, v22
	v_bfe_u32 v0, v20, 16, 1
	v_lshlrev_b64 v[22:23], 11, v[22:23]
	v_add3_u32 v0, v20, v0, s33
	v_lshl_add_u64 v[22:23], s[4:5], 0, v[22:23]
	global_store_short_d16_hi v[22:23], v0, off
	v_bfe_u32 v0, v18, 16, 1
	v_add3_u32 v0, v18, v0, s33
	global_store_short_d16_hi v[22:23], v0, off offset:2048
	v_bfe_u32 v0, v21, 16, 1
	v_add_co_u32_e32 v22, vcc, 0x1000, v22
	v_add3_u32 v0, v21, v0, s33
	s_nop 0
	v_addc_co_u32_e32 v23, vcc, 0, v23, vcc
	global_store_short_d16_hi v[22:23], v0, off
	v_bfe_u32 v0, v19, 16, 1
	v_add3_u32 v0, v19, v0, s33
	s_mov_b64 s[0:1], 0
	global_store_short_d16_hi v[22:23], v0, off offset:2048

; __device__ __forceinline__ float bf2f(u16 h) { return __uint_as_float(((unsigned)h) << 16); }
; __device__ __forceinline__ unsigned pack2(float a, float b) { return (unsigned)f2bf(a) | ((unsigned)f2bf(b) << 16); }
; __device__ __forceinline__ void hyena_lat_job(const Params& p, char* smem, int l, int c) {
;     ...
;         int t0 = tb + 32 * mt + 8 * g;
;         float uu[6];
;         {
;           const uint2 mid = *(const uint2*)&u[t0];
;           uu[0] = t0 > 0 ? bf2f(u[t0 - 1]) : 0.f;
;           uu[1] = __uint_as_float(mid.x << 16); uu[2] = __uint_as_float(mid.x & 0xffff0000u);
;           uu[3] = __uint_as_float(mid.y << 16); uu[4] = __uint_as_float(mid.y & 0xffff0000u);
;           uu[5] = t0 + 4 < 8192 ? bf2f(u[t0 + 4]) : 0.f;
;         }
;         const int zi0 = b * 10240 + (t0 >> 5) * 40 + (t0 & 31);
;         const uint2 zo = *(const uint2*)&zs[zi0];
;         float zold4[4] = {__uint_as_float(zo.x << 16), __uint_as_float(zo.x & 0xffff0000u),
;                           __uint_as_float(zo.y << 16), __uint_as_float(zo.y & 0xffff0000u)};
;         float zn4[4];
; #pragma unroll
;         for (int q = 0; q < 4; ++q) {
;           float gate = bb + w0 * uu[q] + w1 * uu[q + 1] + w2 * uu[q + 2];
;           zn4[q] = gate * (scale * acc[mt][g * 4 + q] + zold4[q] * skip);
;         }
;         if (o == 0) {
;           uint2 zw; zw.x = pack2(zn4[0], zn4[1]); zw.y = pack2(zn4[2], zn4[3]);
;           *(uint2*)&zs[zi0] = zw;
;         } else {
; #pragma unroll
;           for (int q = 0; q < 4; ++q) MIX[(size_t)(b * 8192 + t0 + q) * 1024 + 512 + c] = f2bf(zn4[q]);
;         }
.LBB0_1105:
	v_mov_b32_e32 v20, v232
	v_mov_b32_e32 v21, v233
	v_add_u32_e32 v0, 88, v78
	v_lshrrev_b32_e32 v244, 16, v231
	s_movk_i32 s0, 0x1fa4
	v_cmp_gt_i32_e32 vcc, s0, v78
	v_and_b32_e32 v245, 0xffff, v234
	s_nop 0
	v_cndmask_b32_e32 v245, 0, v245, vcc
	s_waitcnt lgkmcnt(0)
	v_lshlrev_b32_e32 v22, 16, v244
	v_lshlrev_b32_e32 v19, 16, v245
	v_ashrrev_i32_e32 v18, 5, v0
	v_mul_lo_u32 v18, v18, s54
	v_add3_u32 v24, v130, v18, v57
	ds_read_b64 v[34:35], v24
	s_waitcnt lgkmcnt(0)
	v_and_b32_e32 v28, 0xffff0000, v20
	v_mov_b32_e32 v23, v28
	v_lshlrev_b32_e32 v26, 16, v20
	v_lshlrev_b32_e32 v27, 16, v21
	v_pk_fma_f32 v[22:23], v[70:71], v[22:23], v[74:75]
	v_and_b32_e32 v29, 0xffff0000, v21
	v_mov_b32_e32 v18, v27
	v_pk_fma_f32 v[22:23], v[68:69], v[26:27], v[22:23]
	v_pk_fma_f32 v[26:27], v[70:71], v[26:27], v[74:75]
	v_lshlrev_b32_e32 v21, 16, v35
	v_lshlrev_b32_e32 v20, 16, v34
	v_and_b32_e32 v35, 0xffff0000, v35
	v_and_b32_e32 v34, 0xffff0000, v34
	v_pk_fma_f32 v[26:27], v[68:69], v[28:29], v[26:27]
	v_mov_b32_e32 v36, v30
	v_mov_b32_e32 v37, v32
	v_pk_mul_f32 v[20:21], v[66:67], v[20:21]
	v_pk_fma_f32 v[18:19], v[72:73], v[18:19], v[26:27]
	v_mov_b32_e32 v32, v31
	v_pk_mul_f32 v[26:27], v[66:67], v[34:35]
	v_pk_fma_f32 v[22:23], v[72:73], v[28:29], v[22:23]
	v_pk_fma_f32 v[20:21], v[36:37], v[82:83], v[20:21]
	v_pk_fma_f32 v[26:27], v[32:33], v[82:83], v[26:27]
	v_pk_mul_f32 v[20:21], v[22:23], v[20:21]
	v_pk_mul_f32 v[18:19], v[18:19], v[26:27]
	s_and_b64 vcc, exec, s[50:51]
	s_mov_b64 s[0:1], -1
	s_cbranch_vccnz .LBB0_1111
	v_add_u32_e32 v22, v0, v128
	v_ashrrev_i32_e32 v23, 31, v22
	v_bfe_u32 v0, v20, 16, 1
	v_lshlrev_b64 v[22:23], 11, v[22:23]
	v_add3_u32 v0, v20, v0, s33
	v_lshl_add_u64 v[22:23], s[4:5], 0, v[22:23]
	global_store_short_d16_hi v[22:23], v0, off
	v_bfe_u32 v0, v18, 16, 1
	v_add3_u32 v0, v18, v0, s33
	global_store_short_d16_hi v[22:23], v0, off offset:2048
	v_bfe_u32 v0, v21, 16, 1
	v_add_co_u32_e32 v22, vcc, 0x1000, v22
	v_add3_u32 v0, v21, v0, s33
	s_nop 0
	v_addc_co_u32_e32 v23, vcc, 0, v23, vcc
	global_store_short_d16_hi v[22:23], v0, off
	v_bfe_u32 v0, v19, 16, 1
	v_add3_u32 v0, v19, v0, s33
	s_mov_b64 s[0:1], 0
	global_store_short_d16_hi v[22:23], v0, off offset:2048

; __device__ __forceinline__ float bf2f(u16 h) { return __uint_as_float(((unsigned)h) << 16); }
; __device__ __forceinline__ unsigned pack2(float a, float b) { return (unsigned)f2bf(a) | ((unsigned)f2bf(b) << 16); }
; __device__ __forceinline__ void hyena_lat_job(const Params& p, char* smem, int l, int c) {
;     ...
;         int t0 = tb + 32 * mt + 8 * g;
;         float uu[6];
;         {
;           const uint2 mid = *(const uint2*)&u[t0];
;           uu[0] = t0 > 0 ? bf2f(u[t0 - 1]) : 0.f;
;           uu[1] = __uint_as_float(mid.x << 16); uu[2] = __uint_as_float(mid.x & 0xffff0000u);
;           uu[3] = __uint_as_float(mid.y << 16); uu[4] = __uint_as_float(mid.y & 0xffff0000u);
;           uu[5] = t0 + 4 < 8192 ? bf2f(u[t0 + 4]) : 0.f;
;         }
;         const int zi0 = b * 10240 + (t0 >> 5) * 40 + (t0 & 31);
;         const uint2 zo = *(const uint2*)&zs[zi0];
;         float zold4[4] = {__uint_as_float(zo.x << 16), __uint_as_float(zo.x & 0xffff0000u),
;                           __uint_as_float(zo.y << 16), __uint_as_float(zo.y & 0xffff0000u)};
;         float zn4[4];
; #pragma unroll
;         for (int q = 0; q < 4; ++q) {
;           float gate = bb + w0 * uu[q] + w1 * uu[q + 1] + w2 * uu[q + 2];
;           zn4[q] = gate * (scale * acc[mt][g * 4 + q] + zold4[q] * skip);
;         }
;         if (o == 0) {
;           uint2 zw; zw.x = pack2(zn4[0], zn4[1]); zw.y = pack2(zn4[2], zn4[3]);
;           *(uint2*)&zs[zi0] = zw;
;         } else {
; #pragma unroll
;           for (int q = 0; q < 4; ++q) MIX[(size_t)(b * 8192 + t0 + q) * 1024 + 512 + c] = f2bf(zn4[q]);
;         }
.LBB0_1113:
	v_mov_b32_e32 v20, v240
	v_mov_b32_e32 v21, v241
	v_add_u32_e32 v0, 96, v78
	v_lshrrev_b32_e32 v244, 16, v235
	s_movk_i32 s0, 0x1f9c
	v_cmp_gt_i32_e32 vcc, s0, v78
	v_and_b32_e32 v245, 0xffff, v242
	s_nop 0
	v_cndmask_b32_e32 v245, 0, v245, vcc
	s_waitcnt lgkmcnt(0)
	v_lshlrev_b32_e32 v22, 16, v244
	v_lshlrev_b32_e32 v19, 16, v245
	v_ashrrev_i32_e32 v18, 5, v0
	v_mul_lo_u32 v18, v18, s54
	v_add3_u32 v24, v130, v18, v79
	ds_read_b64 v[30:31], v24
	s_waitcnt lgkmcnt(0)
	v_and_b32_e32 v28, 0xffff0000, v20
	v_mov_b32_e32 v23, v28
	v_lshlrev_b32_e32 v26, 16, v20
	v_lshlrev_b32_e32 v27, 16, v21
	v_pk_fma_f32 v[22:23], v[70:71], v[22:23], v[74:75]
	v_and_b32_e32 v29, 0xffff0000, v21
	v_mov_b32_e32 v18, v27
	v_lshlrev_b32_e32 v21, 16, v31
	v_lshlrev_b32_e32 v20, 16, v30
	v_and_b32_e32 v31, 0xffff0000, v31
	v_and_b32_e32 v30, 0xffff0000, v30
	v_pk_fma_f32 v[22:23], v[68:69], v[26:27], v[22:23]
	v_pk_fma_f32 v[26:27], v[70:71], v[26:27], v[74:75]
	v_mov_b32_e32 v32, v2
	v_mov_b32_e32 v33, v4
	v_pk_mul_f32 v[20:21], v[66:67], v[20:21]
	v_pk_fma_f32 v[26:27], v[68:69], v[28:29], v[26:27]
	v_mov_b32_e32 v4, v3
	v_pk_mul_f32 v[2:3], v[66:67], v[30:31]
	v_pk_fma_f32 v[22:23], v[72:73], v[28:29], v[22:23]
	v_pk_fma_f32 v[20:21], v[32:33], v[82:83], v[20:21]
	v_pk_fma_f32 v[18:19], v[72:73], v[18:19], v[26:27]
	v_pk_fma_f32 v[2:3], v[4:5], v[82:83], v[2:3]
	v_pk_mul_f32 v[4:5], v[22:23], v[20:21]
	v_pk_mul_f32 v[2:3], v[18:19], v[2:3]
	s_and_b64 vcc, exec, s[50:51]
	s_mov_b64 s[0:1], -1
	s_cbranch_vccnz .LBB0_1119
	v_add_u32_e32 v18, v0, v128
	v_ashrrev_i32_e32 v19, 31, v18
	v_bfe_u32 v0, v4, 16, 1
	v_lshlrev_b64 v[18:19], 11, v[18:19]
	v_add3_u32 v0, v4, v0, s33
	v_lshl_add_u64 v[18:19], s[4:5], 0, v[18:19]
	global_store_short_d16_hi v[18:19], v0, off
	v_bfe_u32 v0, v2, 16, 1
	v_add3_u32 v0, v2, v0, s33
	global_store_short_d16_hi v[18:19], v0, off offset:2048
	v_bfe_u32 v0, v5, 16, 1
	v_add_co_u32_e32 v18, vcc, 0x1000, v18
	v_add3_u32 v0, v5, v0, s33
	s_nop 0
	v_addc_co_u32_e32 v19, vcc, 0, v19, vcc
	global_store_short_d16_hi v[18:19], v0, off
	v_bfe_u32 v0, v3, 16, 1
	v_add3_u32 v0, v3, v0, s33
	s_mov_b64 s[0:1], 0
	global_store_short_d16_hi v[18:19], v0, off offset:2048

; __device__ __forceinline__ float bf2f(u16 h) { return __uint_as_float(((unsigned)h) << 16); }
; __device__ __forceinline__ unsigned pack2(float a, float b) { return (unsigned)f2bf(a) | ((unsigned)f2bf(b) << 16); }
; __device__ __forceinline__ void hyena_lat_job(const Params& p, char* smem, int l, int c) {
;     ...
;         int t0 = tb + 32 * mt + 8 * g;
;         float uu[6];
;         {
;           const uint2 mid = *(const uint2*)&u[t0];
;           uu[0] = t0 > 0 ? bf2f(u[t0 - 1]) : 0.f;
;           uu[1] = __uint_as_float(mid.x << 16); uu[2] = __uint_as_float(mid.x & 0xffff0000u);
;           uu[3] = __uint_as_float(mid.y << 16); uu[4] = __uint_as_float(mid.y & 0xffff0000u);
;           uu[5] = t0 + 4 < 8192 ? bf2f(u[t0 + 4]) : 0.f;
;         }
;         const int zi0 = b * 10240 + (t0 >> 5) * 40 + (t0 & 31);
;         const uint2 zo = *(const uint2*)&zs[zi0];
;         float zold4[4] = {__uint_as_float(zo.x << 16), __uint_as_float(zo.x & 0xffff0000u),
;                           __uint_as_float(zo.y << 16), __uint_as_float(zo.y & 0xffff0000u)};
;         float zn4[4];
; #pragma unroll
;         for (int q = 0; q < 4; ++q) {
;           float gate = bb + w0 * uu[q] + w1 * uu[q + 1] + w2 * uu[q + 2];
;           zn4[q] = gate * (scale * acc[mt][g * 4 + q] + zold4[q] * skip);
;         }
;         if (o == 0) {
;           uint2 zw; zw.x = pack2(zn4[0], zn4[1]); zw.y = pack2(zn4[2], zn4[3]);
;           *(uint2*)&zs[zi0] = zw;
;         } else {
; #pragma unroll
;           for (int q = 0; q < 4; ++q) MIX[(size_t)(b * 8192 + t0 + q) * 1024 + 512 + c] = f2bf(zn4[q]);
;         }
.LBB0_1121:
	v_mov_b32_e32 v4, v246
	v_mov_b32_e32 v5, v247
	v_add_u32_e32 v0, 104, v78
	v_lshrrev_b32_e32 v244, 16, v243
	s_movk_i32 s0, 0x1f94
	v_cmp_gt_i32_e32 vcc, s0, v78
	v_and_b32_e32 v245, 0xffff, v248
	s_nop 0
	v_cndmask_b32_e32 v245, 0, v245, vcc
	s_waitcnt lgkmcnt(0)
	v_lshlrev_b32_e32 v18, 16, v244
	v_lshlrev_b32_e32 v3, 16, v245
	v_ashrrev_i32_e32 v2, 5, v0
	v_mul_lo_u32 v2, v2, s54
	v_add3_u32 v20, v130, v2, v86
	ds_read_b64 v[26:27], v20
	s_waitcnt lgkmcnt(0)
	v_and_b32_e32 v24, 0xffff0000, v4
	v_mov_b32_e32 v19, v24
	v_lshlrev_b32_e32 v22, 16, v4
	v_lshlrev_b32_e32 v23, 16, v5
	v_pk_fma_f32 v[18:19], v[70:71], v[18:19], v[74:75]
	v_and_b32_e32 v25, 0xffff0000, v5
	v_mov_b32_e32 v2, v23
	v_lshlrev_b32_e32 v5, 16, v27
	v_lshlrev_b32_e32 v4, 16, v26
	v_and_b32_e32 v27, 0xffff0000, v27
	v_and_b32_e32 v26, 0xffff0000, v26
	v_pk_fma_f32 v[18:19], v[68:69], v[22:23], v[18:19]
	v_pk_fma_f32 v[22:23], v[70:71], v[22:23], v[74:75]
	v_mov_b32_e32 v28, v6
	v_mov_b32_e32 v29, v8
	v_pk_mul_f32 v[4:5], v[66:67], v[4:5]
	v_pk_fma_f32 v[22:23], v[68:69], v[24:25], v[22:23]
	v_mov_b32_e32 v8, v7
	v_pk_mul_f32 v[6:7], v[66:67], v[26:27]
	v_pk_fma_f32 v[18:19], v[72:73], v[24:25], v[18:19]
	v_pk_fma_f32 v[4:5], v[28:29], v[82:83], v[4:5]
	v_pk_fma_f32 v[2:3], v[72:73], v[2:3], v[22:23]
	v_pk_fma_f32 v[6:7], v[8:9], v[82:83], v[6:7]
	v_pk_mul_f32 v[4:5], v[18:19], v[4:5]
	v_pk_mul_f32 v[2:3], v[2:3], v[6:7]
	s_and_b64 vcc, exec, s[50:51]
	s_mov_b64 s[0:1], -1
	s_cbranch_vccnz .LBB0_1127
	v_add_u32_e32 v6, v0, v128
	v_ashrrev_i32_e32 v7, 31, v6
	v_bfe_u32 v0, v4, 16, 1
	v_lshlrev_b64 v[6:7], 11, v[6:7]
	v_add3_u32 v0, v4, v0, s33
	v_lshl_add_u64 v[6:7], s[4:5], 0, v[6:7]
	global_store_short_d16_hi v[6:7], v0, off
	v_bfe_u32 v0, v2, 16, 1
	v_add3_u32 v0, v2, v0, s33
	global_store_short_d16_hi v[6:7], v0, off offset:2048
	v_bfe_u32 v0, v5, 16, 1
	v_add_co_u32_e32 v6, vcc, 0x1000, v6
	v_add3_u32 v0, v5, v0, s33
	s_nop 0
	v_addc_co_u32_e32 v7, vcc, 0, v7, vcc
	global_store_short_d16_hi v[6:7], v0, off
	v_bfe_u32 v0, v3, 16, 1
	v_add3_u32 v0, v3, v0, s33
	s_mov_b64 s[0:1], 0
	global_store_short_d16_hi v[6:7], v0, off offset:2048

; __device__ __forceinline__ float bf2f(u16 h) { return __uint_as_float(((unsigned)h) << 16); }
; __device__ __forceinline__ unsigned pack2(float a, float b) { return (unsigned)f2bf(a) | ((unsigned)f2bf(b) << 16); }
; __device__ __forceinline__ void hyena_lat_job(const Params& p, char* smem, int l, int c) {
;     ...
;         int t0 = tb + 32 * mt + 8 * g;
;         float uu[6];
;         {
;           const uint2 mid = *(const uint2*)&u[t0];
;           uu[0] = t0 > 0 ? bf2f(u[t0 - 1]) : 0.f;
;           uu[1] = __uint_as_float(mid.x << 16); uu[2] = __uint_as_float(mid.x & 0xffff0000u);
;           uu[3] = __uint_as_float(mid.y << 16); uu[4] = __uint_as_float(mid.y & 0xffff0000u);
;           uu[5] = t0 + 4 < 8192 ? bf2f(u[t0 + 4]) : 0.f;
;         }
;         const int zi0 = b * 10240 + (t0 >> 5) * 40 + (t0 & 31);
;         const uint2 zo = *(const uint2*)&zs[zi0];
;         float zold4[4] = {__uint_as_float(zo.x << 16), __uint_as_float(zo.x & 0xffff0000u),
;                           __uint_as_float(zo.y << 16), __uint_as_float(zo.y & 0xffff0000u)};
;         float zn4[4];
; #pragma unroll
;         for (int q = 0; q < 4; ++q) {
;           float gate = bb + w0 * uu[q] + w1 * uu[q + 1] + w2 * uu[q + 2];
;           zn4[q] = gate * (scale * acc[mt][g * 4 + q] + zold4[q] * skip);
;         }
;         if (o == 0) {
;           uint2 zw; zw.x = pack2(zn4[0], zn4[1]); zw.y = pack2(zn4[2], zn4[3]);
;           *(uint2*)&zs[zi0] = zw;
;         } else {
; #pragma unroll
;           for (int q = 0; q < 4; ++q) MIX[(size_t)(b * 8192 + t0 + q) * 1024 + 512 + c] = f2bf(zn4[q]);
;         }
.LBB0_1129:
	v_mov_b32_e32 v4, v250
	v_mov_b32_e32 v5, v251
	v_add_u32_e32 v0, 112, v78
	v_lshrrev_b32_e32 v244, 16, v249
	s_movk_i32 s0, 0x1f8c
	v_cmp_gt_i32_e32 vcc, s0, v78
	v_and_b32_e32 v245, 0xffff, v252
	s_nop 0
	v_cndmask_b32_e32 v245, 0, v245, vcc
	s_waitcnt lgkmcnt(0)
	v_lshlrev_b32_e32 v6, 16, v244
	v_lshlrev_b32_e32 v3, 16, v245
	v_ashrrev_i32_e32 v2, 5, v0
	v_mul_lo_u32 v2, v2, s54
	v_add3_u32 v8, v130, v2, v56
	ds_read_b64 v[22:23], v8
	s_waitcnt lgkmcnt(0)
	v_and_b32_e32 v20, 0xffff0000, v4
	v_mov_b32_e32 v7, v20
	v_lshlrev_b32_e32 v18, 16, v4
	v_lshlrev_b32_e32 v19, 16, v5
	v_pk_fma_f32 v[6:7], v[70:71], v[6:7], v[74:75]
	v_and_b32_e32 v21, 0xffff0000, v5
	v_mov_b32_e32 v2, v19
	v_lshlrev_b32_e32 v5, 16, v23
	v_lshlrev_b32_e32 v4, 16, v22
	v_and_b32_e32 v23, 0xffff0000, v23
	v_and_b32_e32 v22, 0xffff0000, v22
	v_pk_fma_f32 v[6:7], v[68:69], v[18:19], v[6:7]
	v_pk_fma_f32 v[18:19], v[70:71], v[18:19], v[74:75]
	v_mov_b32_e32 v24, v10
	v_mov_b32_e32 v25, v12
	v_pk_mul_f32 v[4:5], v[66:67], v[4:5]
	v_pk_fma_f32 v[18:19], v[68:69], v[20:21], v[18:19]
	v_mov_b32_e32 v12, v11
	v_pk_mul_f32 v[10:11], v[66:67], v[22:23]
	v_pk_fma_f32 v[6:7], v[72:73], v[20:21], v[6:7]
	v_pk_fma_f32 v[4:5], v[24:25], v[82:83], v[4:5]
	v_pk_fma_f32 v[2:3], v[72:73], v[2:3], v[18:19]
	v_pk_fma_f32 v[10:11], v[12:13], v[82:83], v[10:11]
	v_pk_mul_f32 v[4:5], v[6:7], v[4:5]
	v_pk_mul_f32 v[2:3], v[2:3], v[10:11]
	s_and_b64 vcc, exec, s[50:51]
	s_mov_b64 s[0:1], -1
	s_cbranch_vccnz .LBB0_1135
	v_add_u32_e32 v6, v0, v128
	v_ashrrev_i32_e32 v7, 31, v6
	v_bfe_u32 v0, v4, 16, 1
	v_lshlrev_b64 v[6:7], 11, v[6:7]
	v_add3_u32 v0, v4, v0, s33
	v_lshl_add_u64 v[6:7], s[4:5], 0, v[6:7]
	global_store_short_d16_hi v[6:7], v0, off
	v_bfe_u32 v0, v2, 16, 1
	v_add3_u32 v0, v2, v0, s33
	global_store_short_d16_hi v[6:7], v0, off offset:2048
	v_bfe_u32 v0, v5, 16, 1
	v_add_co_u32_e32 v6, vcc, 0x1000, v6
	v_add3_u32 v0, v5, v0, s33
	s_nop 0
	v_addc_co_u32_e32 v7, vcc, 0, v7, vcc
	global_store_short_d16_hi v[6:7], v0, off
	v_bfe_u32 v0, v3, 16, 1
	v_add3_u32 v0, v3, v0, s33
	s_mov_b64 s[0:1], 0
	global_store_short_d16_hi v[6:7], v0, off offset:2048

; __device__ __forceinline__ float bf2f(u16 h) { return __uint_as_float(((unsigned)h) << 16); }
; __device__ __forceinline__ unsigned pack2(float a, float b) { return (unsigned)f2bf(a) | ((unsigned)f2bf(b) << 16); }
; __device__ __forceinline__ void hyena_lat_job(const Params& p, char* smem, int l, int c) {
;     ...
;         int t0 = tb + 32 * mt + 8 * g;
;         float uu[6];
;         {
;           const uint2 mid = *(const uint2*)&u[t0];
;           uu[0] = t0 > 0 ? bf2f(u[t0 - 1]) : 0.f;
;           uu[1] = __uint_as_float(mid.x << 16); uu[2] = __uint_as_float(mid.x & 0xffff0000u);
;           uu[3] = __uint_as_float(mid.y << 16); uu[4] = __uint_as_float(mid.y & 0xffff0000u);
;           uu[5] = t0 + 4 < 8192 ? bf2f(u[t0 + 4]) : 0.f;
;         }
;         const int zi0 = b * 10240 + (t0 >> 5) * 40 + (t0 & 31);
;         const uint2 zo = *(const uint2*)&zs[zi0];
;         float zold4[4] = {__uint_as_float(zo.x << 16), __uint_as_float(zo.x & 0xffff0000u),
;                           __uint_as_float(zo.y << 16), __uint_as_float(zo.y & 0xffff0000u)};
;         float zn4[4];
; #pragma unroll
;         for (int q = 0; q < 4; ++q) {
;           float gate = bb + w0 * uu[q] + w1 * uu[q + 1] + w2 * uu[q + 2];
;           zn4[q] = gate * (scale * acc[mt][g * 4 + q] + zold4[q] * skip);
;         }
;         if (o == 0) {
;           uint2 zw; zw.x = pack2(zn4[0], zn4[1]); zw.y = pack2(zn4[2], zn4[3]);
;           *(uint2*)&zs[zi0] = zw;
;         } else {
; #pragma unroll
;           for (int q = 0; q < 4; ++q) MIX[(size_t)(b * 8192 + t0 + q) * 1024 + 512 + c] = f2bf(zn4[q]);
;         }
.LBB0_1137:
	v_mov_b32_e32 v4, v104
	v_mov_b32_e32 v5, v105
	v_add_u32_e32 v0, 120, v78
	v_lshrrev_b32_e32 v244, 16, v253
	s_movk_i32 s0, 0x1f84
	v_cmp_gt_i32_e32 vcc, s0, v78
	v_and_b32_e32 v245, 0xffff, v254
	s_nop 0
	v_cndmask_b32_e32 v245, 0, v245, vcc
	s_waitcnt lgkmcnt(0)
	v_lshlrev_b32_e32 v6, 16, v244
	v_lshlrev_b32_e32 v3, 16, v245
	v_ashrrev_i32_e32 v2, 5, v0
	v_mul_lo_u32 v2, v2, s54
	v_add3_u32 v8, v130, v2, v57
	ds_read_b64 v[18:19], v8
	s_waitcnt lgkmcnt(0)
	v_and_b32_e32 v12, 0xffff0000, v4
	v_mov_b32_e32 v7, v12
	v_lshlrev_b32_e32 v10, 16, v4
	v_lshlrev_b32_e32 v11, 16, v5
	v_pk_fma_f32 v[6:7], v[70:71], v[6:7], v[74:75]
	v_and_b32_e32 v13, 0xffff0000, v5
	v_mov_b32_e32 v2, v11
	v_pk_fma_f32 v[6:7], v[68:69], v[10:11], v[6:7]
	v_pk_fma_f32 v[10:11], v[70:71], v[10:11], v[74:75]
	v_lshlrev_b32_e32 v5, 16, v19
	v_lshlrev_b32_e32 v4, 16, v18
	v_and_b32_e32 v19, 0xffff0000, v19
	v_and_b32_e32 v18, 0xffff0000, v18
	v_pk_fma_f32 v[10:11], v[68:69], v[12:13], v[10:11]
	v_mov_b32_e32 v20, v14
	v_mov_b32_e32 v21, v16
	v_pk_mul_f32 v[4:5], v[66:67], v[4:5]
	v_pk_fma_f32 v[2:3], v[72:73], v[2:3], v[10:11]
	v_mov_b32_e32 v16, v15
	v_pk_mul_f32 v[10:11], v[66:67], v[18:19]
	v_pk_fma_f32 v[6:7], v[72:73], v[12:13], v[6:7]
	v_pk_fma_f32 v[4:5], v[20:21], v[82:83], v[4:5]
	v_pk_fma_f32 v[10:11], v[16:17], v[82:83], v[10:11]
	v_pk_mul_f32 v[4:5], v[6:7], v[4:5]
	v_pk_mul_f32 v[2:3], v[2:3], v[10:11]
	s_and_b64 vcc, exec, s[50:51]
	s_mov_b64 s[0:1], -1
	s_cbranch_vccnz .LBB0_1143
	v_add_u32_e32 v6, v0, v128
	v_ashrrev_i32_e32 v7, 31, v6
	v_bfe_u32 v0, v4, 16, 1
	v_lshlrev_b64 v[6:7], 11, v[6:7]
	v_add3_u32 v0, v4, v0, s33
	v_lshl_add_u64 v[6:7], s[4:5], 0, v[6:7]
	global_store_short_d16_hi v[6:7], v0, off
	v_bfe_u32 v0, v2, 16, 1
	v_add3_u32 v0, v2, v0, s33
	global_store_short_d16_hi v[6:7], v0, off offset:2048
	v_bfe_u32 v0, v5, 16, 1
	v_add_co_u32_e32 v6, vcc, 0x1000, v6
	v_add3_u32 v0, v5, v0, s33
	s_nop 0
	v_addc_co_u32_e32 v7, vcc, 0, v7, vcc
	global_store_short_d16_hi v[6:7], v0, off
	v_bfe_u32 v0, v3, 16, 1
	v_add3_u32 v0, v3, v0, s33
	global_store_short_d16_hi v[6:7], v0, off offset:2048
	s_cbranch_execnz .LBB0_982
	s_branch .LBB0_1144
